# v024: v022 + GEMM main-loop headers issue their LDS fragment reads first (literal address adds), scalar tile bookkeeping moved after the reads
# speedup vs baseline: 1.0032x; 1.0032x over previous
; #define PG8_STAGE(bufoff, gbase, voff) do { _Pragma("unroll") for (int _i = 0; _i < 2; ++_i) \
;         __builtin_amdgcn_global_load_lds((const unsigned*)((const char*)(gbase) + (voff)[_i]), (PG8_LAS unsigned*)(lds + (bufoff) + ldsw + _i * 8192), 16, 0, 0); } while (0)
; #define PG8_LDA(dst, b, h) do { _Pragma("unroll") for (int m = 0; m < 4; ++m) _Pragma("unroll") for (int k = 0; k < 2; ++k) dst[m][k] = *(const PG8_LAS bf16x8*)(lds + PG8_SA(b, h) + aoff + m * 2048 + k * 1024); } while (0)
; #define PG8_LDB(dst, b, h) do { _Pragma("unroll") for (int n = 0; n < 2; ++n) _Pragma("unroll") for (int k = 0; k < 2; ++k) dst[n][k] = *(const PG8_LAS bf16x8*)(lds + PG8_SB(b, h) + boff + n * 2048 + k * 1024); } while (0)
; #define PG8_MMA(ai, bj, At, Bt) do { __builtin_amdgcn_s_setprio(1); _Pragma("unroll") for (int m = 0; m < 4; ++m) _Pragma("unroll") for (int n = 0; n < 2; ++n) _Pragma("unroll") for (int k = 0; k < 2; ++k) \
;         acc[ai][bj][m][n] = __builtin_amdgcn_mfma_f32_16x16x32_bf16(Bt[n][k], At[m][k], acc[ai][bj][m][n], 0, 0, 0); __builtin_amdgcn_s_setprio(0); } while (0)
; #define PG8_WAIT_V(n) asm volatile("s_waitcnt vmcnt(" #n ")" ::: "memory")
; #define PG8_BAR __builtin_amdgcn_s_barrier()
; template <class Epi, class Sched, bool ALIGN_EPI = false, bool SP2 = false>
; __device__ __forceinline__ void gemm_phase(PG8_LAS unsigned char* lds, const Gemm g, const Sched& S, const Epi& E, int tid_) {
;     ...
;         for (int t = 0; t < nt; t += 2) {
;             const bool last = (t == nt - 2);
;             const char* a1 = cA + (size_t)(t + 1) * kstep;
;             const char* a2 = last ? nA : cA + (size_t)(t + 2) * kstep; const char* b2 = last ? nB : cB + (size_t)(t + 2) * kstep;
;             const char* a3 = a2 + kstep; const char* b3 = b2 + kstep;
;             if (last && has_next) S.a_ready(nxt);
;             if constexpr (SP2) {
;             PG8_LDB(B0, 0, 0); PG8_LDB(B1, 0, 1); PG8_SCHED; PG8_LDA(At, 0, 0); PG8_STAGE(PG8_SA(1, 1), a1 + hstep, voffA);
;             PG8_WAIT_V(8); PG8_WAIT_L(0); PG8_BAR; PG8_MMA(0, 0, At, B0); PG8_MMA(0, 1, At, B1); PG8_BAR; PG8_SCHED;
;             PG8_LDA(At, 0, 1); PG8_STAGE(PG8_SB(0, 0), b2, voffB); PG8_STAGE(PG8_SB(0, 1), b2 + hstep, voffB); PG8_STAGE(PG8_SA(0, 0), a2, voffA);
;             PG8_WAIT_V(8); PG8_WAIT_L(0); PG8_BAR; PG8_MMA(1, 0, At, B0); PG8_MMA(1, 1, At, B1); PG8_BAR; PG8_SCHED;
.LBB0_226:
	v_add_u32_e32 v140, 0x10000, v143
	ds_read_b128 v[146:149], v140
	ds_read_b128 v[150:153], v140 offset:1024
	ds_read_b128 v[154:157], v140 offset:2048
	ds_read_b128 v[158:161], v140 offset:3072
	v_add_u32_e32 v140, 0x14000, v143
	ds_read_b128 v[162:165], v140
	ds_read_b128 v[166:169], v140 offset:1024
	ds_read_b128 v[170:173], v140 offset:2048
	ds_read_b128 v[174:177], v140 offset:3072
	s_add_i32 s91, s64, 2
	s_add_u32 s21, s70, 0x80
	s_addc_u32 s65, s71, 0
	s_add_i32 s94, 0, 0x10000
	s_cmp_eq_u32 s55, s64
	s_cselect_b32 s65, s43, s65
	s_cselect_b32 s64, s42, s21
	s_cselect_b32 s93, s61, s81
	s_cselect_b32 s92, s60, s80
	s_add_i32 s21, 0, 0x14000
	v_lshl_add_u64 v[140:141], s[70:71], 0, v[138:139]
	s_add_i32 m0, s11, 0xc000
	ds_read_b128 v[178:181], v145
	ds_read_b128 v[182:185], v145 offset:1024
	ds_read_b128 v[186:189], v145 offset:2048
	ds_read_b128 v[200:203], v145 offset:3072
	ds_read_b128 v[204:207], v145 offset:4096
	ds_read_b128 v[208:211], v145 offset:5120
	ds_read_b128 v[214:217], v145 offset:6144
	ds_read_b128 v[232:235], v145 offset:7168
	global_load_lds_dwordx4 v[140:141], off
	v_lshl_add_u64 v[140:141], s[70:71], 0, v[136:137]
	s_add_i32 m0, s11, 0xe000
	s_nop 0
	global_load_lds_dwordx4 v[140:141], off
	s_waitcnt vmcnt(8)
	s_waitcnt lgkmcnt(0)
	s_barrier
	s_setprio 1
	s_waitcnt lgkmcnt(0)
	v_mfma_f32_16x16x32_bf16 v[126:129], v[146:149], v[178:181], v[126:129]
	v_mfma_f32_16x16x32_bf16 v[122:125], v[154:157], v[178:181], v[122:125]
	v_mfma_f32_16x16x32_bf16 v[110:113], v[146:149], v[186:189], v[110:113]
	v_mfma_f32_16x16x32_bf16 v[106:109], v[154:157], v[186:189], v[106:109]
	v_mfma_f32_16x16x32_bf16 v[94:97], v[146:149], v[204:207], v[94:97]
	v_mfma_f32_16x16x32_bf16 v[90:93], v[154:157], v[204:207], v[90:93]
	v_mfma_f32_16x16x32_bf16 v[78:81], v[146:149], v[214:217], v[78:81]
	v_mfma_f32_16x16x32_bf16 v[74:77], v[154:157], v[214:217], v[74:77]
	v_mfma_f32_16x16x32_bf16 v[126:129], v[150:153], v[182:185], v[126:129]
	v_mfma_f32_16x16x32_bf16 v[122:125], v[158:161], v[182:185], v[122:125]
	v_mfma_f32_16x16x32_bf16 v[110:113], v[150:153], v[200:203], v[110:113]
	v_mfma_f32_16x16x32_bf16 v[106:109], v[158:161], v[200:203], v[106:109]
	v_mfma_f32_16x16x32_bf16 v[94:97], v[150:153], v[208:211], v[94:97]
	v_mfma_f32_16x16x32_bf16 v[90:93], v[158:161], v[208:211], v[90:93]
	v_mfma_f32_16x16x32_bf16 v[78:81], v[150:153], v[232:235], v[78:81]
	v_mfma_f32_16x16x32_bf16 v[74:77], v[158:161], v[232:235], v[74:77]
	s_setprio 0
	s_setprio 1
	v_mfma_f32_16x16x32_bf16 v[118:121], v[162:165], v[178:181], v[118:121]
	v_mfma_f32_16x16x32_bf16 v[114:117], v[170:173], v[178:181], v[114:117]
	v_mfma_f32_16x16x32_bf16 v[102:105], v[162:165], v[186:189], v[102:105]
	v_mfma_f32_16x16x32_bf16 v[98:101], v[170:173], v[186:189], v[98:101]
	v_mfma_f32_16x16x32_bf16 v[86:89], v[162:165], v[204:207], v[86:89]
	v_mfma_f32_16x16x32_bf16 v[82:85], v[170:173], v[204:207], v[82:85]
	v_mfma_f32_16x16x32_bf16 v[70:73], v[162:165], v[214:217], v[70:73]
	v_mfma_f32_16x16x32_bf16 v[66:69], v[170:173], v[214:217], v[66:69]
	v_mfma_f32_16x16x32_bf16 v[118:121], v[166:169], v[182:185], v[118:121]
	v_mfma_f32_16x16x32_bf16 v[114:117], v[174:177], v[182:185], v[114:117]
	v_mfma_f32_16x16x32_bf16 v[102:105], v[166:169], v[200:203], v[102:105]
	v_mfma_f32_16x16x32_bf16 v[98:101], v[174:177], v[200:203], v[98:101]
	v_mfma_f32_16x16x32_bf16 v[86:89], v[166:169], v[208:211], v[86:89]
	v_mfma_f32_16x16x32_bf16 v[82:85], v[174:177], v[208:211], v[82:85]
	v_mfma_f32_16x16x32_bf16 v[70:73], v[166:169], v[232:235], v[70:73]
	v_mfma_f32_16x16x32_bf16 v[66:69], v[174:177], v[232:235], v[66:69]
	s_setprio 0
	s_barrier
	s_add_i32 s94, s94, s9
	v_lshl_add_u64 v[140:141], s[92:93], 0, v[0:1]
	s_mov_b32 m0, s94
	ds_read_b128 v[178:181], v145 offset:16384
	ds_read_b128 v[182:185], v145 offset:17408
	ds_read_b128 v[186:189], v145 offset:18432
	ds_read_b128 v[200:203], v145 offset:19456
	ds_read_b128 v[204:207], v145 offset:20480
	ds_read_b128 v[208:211], v145 offset:21504
	ds_read_b128 v[214:217], v145 offset:22528
	ds_read_b128 v[232:235], v145 offset:23552
	global_load_lds_dwordx4 v[140:141], off
	s_add_i32 m0, s94, 0x2000
	v_lshl_add_u64 v[190:191], s[92:93], 0, v[134:135]
	s_add_u32 s92, s92, s38
	s_addc_u32 s93, s93, s39
	s_add_i32 s21, s21, s9
	global_load_lds_dwordx4 v[190:191], off
	v_lshl_add_u64 v[236:237], s[92:93], 0, v[0:1]
	s_mov_b32 m0, s21
	v_lshl_add_u64 v[238:239], s[92:93], 0, v[134:135]
	global_load_lds_dwordx4 v[236:237], off
	s_add_i32 m0, s21, 0x2000
	v_lshl_add_u64 v[240:241], s[64:65], 0, v[130:131]
	global_load_lds_dwordx4 v[238:239], off
	s_mov_b32 m0, s11
	v_lshl_add_u64 v[242:243], s[64:65], 0, v[132:133]
	global_load_lds_dwordx4 v[240:241], off
	s_mov_b32 m0, s12
	s_nop 0
	global_load_lds_dwordx4 v[242:243], off
	s_waitcnt vmcnt(8)
	s_waitcnt lgkmcnt(0)
	s_barrier
; #define PG8_STAGE(bufoff, gbase, voff) do { _Pragma("unroll") for (int _i = 0; _i < 2; ++_i) \
;         __builtin_amdgcn_global_load_lds((const unsigned*)((const char*)(gbase) + (voff)[_i]), (PG8_LAS unsigned*)(lds + (bufoff) + ldsw + _i * 8192), 16, 0, 0); } while (0)
; #define PG8_LDA(dst, b, h) do { _Pragma("unroll") for (int m = 0; m < 4; ++m) _Pragma("unroll") for (int k = 0; k < 2; ++k) dst[m][k] = *(const PG8_LAS bf16x8*)(lds + PG8_SA(b, h) + aoff + m * 2048 + k * 1024); } while (0)
; #define PG8_LDB(dst, b, h) do { _Pragma("unroll") for (int n = 0; n < 2; ++n) _Pragma("unroll") for (int k = 0; k < 2; ++k) dst[n][k] = *(const PG8_LAS bf16x8*)(lds + PG8_SB(b, h) + boff + n * 2048 + k * 1024); } while (0)
; #define PG8_MMA(ai, bj, At, Bt) do { __builtin_amdgcn_s_setprio(1); _Pragma("unroll") for (int m = 0; m < 4; ++m) _Pragma("unroll") for (int n = 0; n < 2; ++n) _Pragma("unroll") for (int k = 0; k < 2; ++k) \
;         acc[ai][bj][m][n] = __builtin_amdgcn_mfma_f32_16x16x32_bf16(Bt[n][k], At[m][k], acc[ai][bj][m][n], 0, 0, 0); __builtin_amdgcn_s_setprio(0); } while (0)
; #define PG8_WAIT_V(n) asm volatile("s_waitcnt vmcnt(" #n ")" ::: "memory")
; #define PG8_WAIT_L(n) asm volatile("s_waitcnt lgkmcnt(" #n ")" ::: "memory")
; #define PG8_BAR __builtin_amdgcn_s_barrier()
; #define PG8_SCHED __builtin_amdgcn_sched_barrier(0)
; template <class Epi, class Sched, bool ALIGN_EPI = false, bool SP2 = false>
; __device__ __forceinline__ void gemm_phase(PG8_LAS unsigned char* lds, const Gemm g, const Sched& S, const Epi& E, int tid_) {
;     ...
;             PG8_WAIT_V(8); PG8_WAIT_L(0); PG8_BAR; PG8_MMA(1, 0, At, B0); PG8_MMA(1, 1, At, B1); PG8_BAR; PG8_SCHED;
;             PG8_LDB(B0, 1, 0); PG8_LDB(B1, 1, 1); PG8_SCHED; PG8_LDA(At, 1, 0); PG8_STAGE(PG8_SA(0, 1), a2 + hstep, voffA);
;             PG8_WAIT_V(8); PG8_WAIT_L(0); PG8_BAR; PG8_MMA(0, 0, At, B0); PG8_MMA(0, 1, At, B1); PG8_BAR; PG8_SCHED;
;             PG8_LDA(At, 1, 1); PG8_STAGE(PG8_SB(1, 0), b3, voffB); PG8_STAGE(PG8_SB(1, 1), b3 + hstep, voffB); PG8_STAGE(PG8_SA(1, 0), a3, voffA);
	s_setprio 1
	s_waitcnt lgkmcnt(0)
	v_mfma_f32_16x16x32_bf16 v[62:65], v[146:149], v[178:181], v[62:65]
	v_mfma_f32_16x16x32_bf16 v[58:61], v[154:157], v[178:181], v[58:61]
	v_mfma_f32_16x16x32_bf16 v[46:49], v[146:149], v[186:189], v[46:49]
	v_mfma_f32_16x16x32_bf16 v[42:45], v[154:157], v[186:189], v[42:45]
	v_mfma_f32_16x16x32_bf16 v[30:33], v[146:149], v[204:207], v[30:33]
	v_mfma_f32_16x16x32_bf16 v[26:29], v[154:157], v[204:207], v[26:29]
	v_mfma_f32_16x16x32_bf16 v[14:17], v[146:149], v[214:217], v[14:17]
	v_mfma_f32_16x16x32_bf16 v[10:13], v[154:157], v[214:217], v[10:13]
	v_mfma_f32_16x16x32_bf16 v[62:65], v[150:153], v[182:185], v[62:65]
	v_mfma_f32_16x16x32_bf16 v[58:61], v[158:161], v[182:185], v[58:61]
	v_mfma_f32_16x16x32_bf16 v[46:49], v[150:153], v[200:203], v[46:49]
	v_mfma_f32_16x16x32_bf16 v[42:45], v[158:161], v[200:203], v[42:45]
	v_mfma_f32_16x16x32_bf16 v[30:33], v[150:153], v[208:211], v[30:33]
	v_mfma_f32_16x16x32_bf16 v[26:29], v[158:161], v[208:211], v[26:29]
	v_mfma_f32_16x16x32_bf16 v[14:17], v[150:153], v[232:235], v[14:17]
	v_mfma_f32_16x16x32_bf16 v[10:13], v[158:161], v[232:235], v[10:13]
	s_setprio 0
	s_setprio 1
	v_mfma_f32_16x16x32_bf16 v[54:57], v[162:165], v[178:181], v[54:57]
	v_mfma_f32_16x16x32_bf16 v[50:53], v[170:173], v[178:181], v[50:53]
	v_mfma_f32_16x16x32_bf16 v[38:41], v[162:165], v[186:189], v[38:41]
	v_mfma_f32_16x16x32_bf16 v[34:37], v[170:173], v[186:189], v[34:37]
	v_mfma_f32_16x16x32_bf16 v[22:25], v[162:165], v[204:207], v[22:25]
	v_mfma_f32_16x16x32_bf16 v[18:21], v[170:173], v[204:207], v[18:21]
	v_mfma_f32_16x16x32_bf16 v[6:9], v[162:165], v[214:217], v[6:9]
	v_mfma_f32_16x16x32_bf16 v[2:5], v[170:173], v[214:217], v[2:5]
	v_mfma_f32_16x16x32_bf16 v[54:57], v[166:169], v[182:185], v[54:57]
	v_mfma_f32_16x16x32_bf16 v[50:53], v[174:177], v[182:185], v[50:53]
	v_mfma_f32_16x16x32_bf16 v[38:41], v[166:169], v[200:203], v[38:41]
	v_mfma_f32_16x16x32_bf16 v[34:37], v[174:177], v[200:203], v[34:37]
	v_mfma_f32_16x16x32_bf16 v[22:25], v[166:169], v[208:211], v[22:25]
	v_mfma_f32_16x16x32_bf16 v[18:21], v[174:177], v[208:211], v[18:21]
	v_mfma_f32_16x16x32_bf16 v[6:9], v[166:169], v[232:235], v[6:9]
	v_mfma_f32_16x16x32_bf16 v[2:5], v[174:177], v[232:235], v[2:5]
	s_setprio 0
	s_barrier
	s_add_i32 s21, 0, 0x18000
	s_add_i32 s92, 0, 0x1c000
	v_add_u32_e32 v158, s21, v143
	v_add_u32_e32 v174, s92, v143
	ds_read_b128 v[146:149], v158
	ds_read_b128 v[150:153], v158 offset:1024
	ds_read_b128 v[154:157], v158 offset:2048
	ds_read_b128 v[158:161], v158 offset:3072
	ds_read_b128 v[162:165], v174
	ds_read_b128 v[166:169], v174 offset:1024
	ds_read_b128 v[170:173], v174 offset:2048
	ds_read_b128 v[174:177], v174 offset:3072
	s_add_u32 s64, s64, s38
	s_addc_u32 s65, s65, s39
	s_mov_b32 m0, s13
	v_lshl_add_u64 v[244:245], s[64:65], 0, v[130:131]
	ds_read_b128 v[178:181], v145 offset:32768
	ds_read_b128 v[182:185], v145 offset:33792
	ds_read_b128 v[186:189], v145 offset:34816
	ds_read_b128 v[200:203], v145 offset:35840
	ds_read_b128 v[204:207], v145 offset:36864
	ds_read_b128 v[208:211], v145 offset:37888
	ds_read_b128 v[214:217], v145 offset:38912
	ds_read_b128 v[232:235], v145 offset:39936
	global_load_lds_dwordx4 v[244:245], off
	v_lshl_add_u64 v[244:245], s[64:65], 0, v[132:133]
	s_mov_b32 m0, s14
	s_nop 0
	global_load_lds_dwordx4 v[244:245], off
	s_waitcnt vmcnt(8)
	s_waitcnt lgkmcnt(0)
	s_barrier
	s_setprio 1
	s_waitcnt lgkmcnt(0)
	v_mfma_f32_16x16x32_bf16 v[126:129], v[146:149], v[178:181], v[126:129]
	v_mfma_f32_16x16x32_bf16 v[122:125], v[154:157], v[178:181], v[122:125]
	v_mfma_f32_16x16x32_bf16 v[110:113], v[146:149], v[186:189], v[110:113]
	v_mfma_f32_16x16x32_bf16 v[106:109], v[154:157], v[186:189], v[106:109]
	v_mfma_f32_16x16x32_bf16 v[94:97], v[146:149], v[204:207], v[94:97]
	v_mfma_f32_16x16x32_bf16 v[90:93], v[154:157], v[204:207], v[90:93]
	v_mfma_f32_16x16x32_bf16 v[78:81], v[146:149], v[214:217], v[78:81]
	v_mfma_f32_16x16x32_bf16 v[74:77], v[154:157], v[214:217], v[74:77]
	v_mfma_f32_16x16x32_bf16 v[126:129], v[150:153], v[182:185], v[126:129]
	v_mfma_f32_16x16x32_bf16 v[122:125], v[158:161], v[182:185], v[122:125]
	v_mfma_f32_16x16x32_bf16 v[110:113], v[150:153], v[200:203], v[110:113]
	v_mfma_f32_16x16x32_bf16 v[106:109], v[158:161], v[200:203], v[106:109]
	v_mfma_f32_16x16x32_bf16 v[94:97], v[150:153], v[208:211], v[94:97]
	v_mfma_f32_16x16x32_bf16 v[90:93], v[158:161], v[208:211], v[90:93]
	v_mfma_f32_16x16x32_bf16 v[78:81], v[150:153], v[232:235], v[78:81]
	v_mfma_f32_16x16x32_bf16 v[74:77], v[158:161], v[232:235], v[74:77]
	s_setprio 0
	s_setprio 1
	v_mfma_f32_16x16x32_bf16 v[118:121], v[162:165], v[178:181], v[118:121]
	v_mfma_f32_16x16x32_bf16 v[114:117], v[170:173], v[178:181], v[114:117]
	v_mfma_f32_16x16x32_bf16 v[102:105], v[162:165], v[186:189], v[102:105]
	v_mfma_f32_16x16x32_bf16 v[98:101], v[170:173], v[186:189], v[98:101]
	v_mfma_f32_16x16x32_bf16 v[86:89], v[162:165], v[204:207], v[86:89]
	v_mfma_f32_16x16x32_bf16 v[82:85], v[170:173], v[204:207], v[82:85]
	v_mfma_f32_16x16x32_bf16 v[70:73], v[162:165], v[214:217], v[70:73]
	v_mfma_f32_16x16x32_bf16 v[66:69], v[170:173], v[214:217], v[66:69]
	v_mfma_f32_16x16x32_bf16 v[118:121], v[166:169], v[182:185], v[118:121]
	v_mfma_f32_16x16x32_bf16 v[114:117], v[174:177], v[182:185], v[114:117]
	v_mfma_f32_16x16x32_bf16 v[102:105], v[166:169], v[200:203], v[102:105]
	v_mfma_f32_16x16x32_bf16 v[98:101], v[174:177], v[200:203], v[98:101]
	v_mfma_f32_16x16x32_bf16 v[86:89], v[166:169], v[208:211], v[86:89]
	v_mfma_f32_16x16x32_bf16 v[82:85], v[174:177], v[208:211], v[82:85]
	v_mfma_f32_16x16x32_bf16 v[70:73], v[166:169], v[232:235], v[70:73]
	v_mfma_f32_16x16x32_bf16 v[66:69], v[174:177], v[232:235], v[66:69]
	s_setprio 0
	s_barrier
; #define PG8_STAGE(bufoff, gbase, voff) do { _Pragma("unroll") for (int _i = 0; _i < 2; ++_i) \
;         __builtin_amdgcn_global_load_lds((const unsigned*)((const char*)(gbase) + (voff)[_i]), (PG8_LAS unsigned*)(lds + (bufoff) + ldsw + _i * 8192), 16, 0, 0); } while (0)
; #define PG8_LDA(dst, b, h) do { _Pragma("unroll") for (int m = 0; m < 4; ++m) _Pragma("unroll") for (int k = 0; k < 2; ++k) dst[m][k] = *(const PG8_LAS bf16x8*)(lds + PG8_SA(b, h) + aoff + m * 2048 + k * 1024); } while (0)
; #define PG8_MMA(ai, bj, At, Bt) do { __builtin_amdgcn_s_setprio(1); _Pragma("unroll") for (int m = 0; m < 4; ++m) _Pragma("unroll") for (int n = 0; n < 2; ++n) _Pragma("unroll") for (int k = 0; k < 2; ++k) \
;         acc[ai][bj][m][n] = __builtin_amdgcn_mfma_f32_16x16x32_bf16(Bt[n][k], At[m][k], acc[ai][bj][m][n], 0, 0, 0); __builtin_amdgcn_s_setprio(0); } while (0)
; #define PG8_WAIT_V(n) asm volatile("s_waitcnt vmcnt(" #n ")" ::: "memory")
; #define PG8_WAIT_L(n) asm volatile("s_waitcnt lgkmcnt(" #n ")" ::: "memory")
; #define PG8_BAR __builtin_amdgcn_s_barrier()
; #define PG8_SCHED __builtin_amdgcn_sched_barrier(0)
; template <class Epi, class Sched, bool ALIGN_EPI = false, bool SP2 = false>
; __device__ __forceinline__ void gemm_phase(PG8_LAS unsigned char* lds, const Gemm g, const Sched& S, const Epi& E, int tid_) {
;     ...
;             PG8_LDA(At, 1, 1); PG8_STAGE(PG8_SB(1, 0), b3, voffB); PG8_STAGE(PG8_SB(1, 1), b3 + hstep, voffB); PG8_STAGE(PG8_SA(1, 0), a3, voffA);
;             PG8_WAIT_V(8); PG8_WAIT_L(0); PG8_BAR; PG8_MMA(1, 0, At, B0); PG8_MMA(1, 1, At, B1); PG8_BAR; PG8_SCHED;
	s_add_i32 s21, s21, s9
	v_lshl_add_u64 v[140:141], v[140:141], 0, s[28:29]
	s_mov_b32 m0, s21
	ds_read_b128 v[178:181], v145 offset:49152
	ds_read_b128 v[182:185], v145 offset:50176
	ds_read_b128 v[186:189], v145 offset:51200
	ds_read_b128 v[200:203], v145 offset:52224
	ds_read_b128 v[204:207], v145 offset:53248
	ds_read_b128 v[208:211], v145 offset:54272
	ds_read_b128 v[214:217], v145 offset:55296
	ds_read_b128 v[232:235], v145 offset:56320
	global_load_lds_dwordx4 v[140:141], off
	v_lshl_add_u64 v[140:141], v[190:191], 0, s[28:29]
	s_add_i32 m0, s21, 0x2000
	s_add_i32 s21, s92, s9
	global_load_lds_dwordx4 v[140:141], off
	v_lshl_add_u64 v[140:141], v[236:237], 0, s[28:29]
	s_mov_b32 m0, s21
	s_nop 0
	global_load_lds_dwordx4 v[140:141], off
	v_lshl_add_u64 v[140:141], v[238:239], 0, s[28:29]
	s_add_i32 m0, s21, 0x2000
	s_nop 0
	global_load_lds_dwordx4 v[140:141], off
	v_lshl_add_u64 v[140:141], v[240:241], 0, s[28:29]
	s_mov_b32 m0, s37
	s_nop 0
	global_load_lds_dwordx4 v[140:141], off
	v_lshl_add_u64 v[140:141], v[242:243], 0, s[28:29]
	s_mov_b32 m0, s69
	s_nop 0
	global_load_lds_dwordx4 v[140:141], off
	s_waitcnt vmcnt(8)
	s_waitcnt lgkmcnt(0)
	s_barrier
	s_setprio 1
	s_waitcnt lgkmcnt(0)
	v_mfma_f32_16x16x32_bf16 v[62:65], v[146:149], v[178:181], v[62:65]
	v_mfma_f32_16x16x32_bf16 v[58:61], v[154:157], v[178:181], v[58:61]
	v_mfma_f32_16x16x32_bf16 v[46:49], v[146:149], v[186:189], v[46:49]
	v_mfma_f32_16x16x32_bf16 v[42:45], v[154:157], v[186:189], v[42:45]
	v_mfma_f32_16x16x32_bf16 v[30:33], v[146:149], v[204:207], v[30:33]
	v_mfma_f32_16x16x32_bf16 v[26:29], v[154:157], v[204:207], v[26:29]
	v_mfma_f32_16x16x32_bf16 v[14:17], v[146:149], v[214:217], v[14:17]
	v_mfma_f32_16x16x32_bf16 v[10:13], v[154:157], v[214:217], v[10:13]
	v_mfma_f32_16x16x32_bf16 v[62:65], v[150:153], v[182:185], v[62:65]
	v_mfma_f32_16x16x32_bf16 v[58:61], v[158:161], v[182:185], v[58:61]
	v_mfma_f32_16x16x32_bf16 v[46:49], v[150:153], v[200:203], v[46:49]
	v_mfma_f32_16x16x32_bf16 v[42:45], v[158:161], v[200:203], v[42:45]
	v_mfma_f32_16x16x32_bf16 v[30:33], v[150:153], v[208:211], v[30:33]
	v_mfma_f32_16x16x32_bf16 v[26:29], v[158:161], v[208:211], v[26:29]
	v_mfma_f32_16x16x32_bf16 v[14:17], v[150:153], v[232:235], v[14:17]
	v_mfma_f32_16x16x32_bf16 v[10:13], v[158:161], v[232:235], v[10:13]
	s_setprio 0
	s_setprio 1
	v_mfma_f32_16x16x32_bf16 v[54:57], v[162:165], v[178:181], v[54:57]
	v_mfma_f32_16x16x32_bf16 v[50:53], v[170:173], v[178:181], v[50:53]
	v_mfma_f32_16x16x32_bf16 v[38:41], v[162:165], v[186:189], v[38:41]
	v_mfma_f32_16x16x32_bf16 v[34:37], v[170:173], v[186:189], v[34:37]
	v_mfma_f32_16x16x32_bf16 v[22:25], v[162:165], v[204:207], v[22:25]
	v_mfma_f32_16x16x32_bf16 v[18:21], v[170:173], v[204:207], v[18:21]
	v_mfma_f32_16x16x32_bf16 v[6:9], v[162:165], v[214:217], v[6:9]
	v_mfma_f32_16x16x32_bf16 v[2:5], v[170:173], v[214:217], v[2:5]
	v_mfma_f32_16x16x32_bf16 v[54:57], v[166:169], v[182:185], v[54:57]
	v_mfma_f32_16x16x32_bf16 v[50:53], v[174:177], v[182:185], v[50:53]
	v_mfma_f32_16x16x32_bf16 v[38:41], v[166:169], v[200:203], v[38:41]
	v_mfma_f32_16x16x32_bf16 v[34:37], v[174:177], v[200:203], v[34:37]
	v_mfma_f32_16x16x32_bf16 v[22:25], v[166:169], v[208:211], v[22:25]
	v_mfma_f32_16x16x32_bf16 v[18:21], v[174:177], v[208:211], v[18:21]
	v_mfma_f32_16x16x32_bf16 v[6:9], v[166:169], v[232:235], v[6:9]
	v_mfma_f32_16x16x32_bf16 v[2:5], v[174:177], v[232:235], v[2:5]
	s_setprio 0
	s_barrier
	s_add_u32 s80, s80, 0x100
	s_addc_u32 s81, s81, 0
	s_add_u32 s70, s70, 0x100
	s_addc_u32 s71, s71, 0
	s_cmp_ge_i32 s91, s90
	s_mov_b32 s64, s91
	s_cbranch_scc0 .LBB0_226
	s_and_b64 vcc, exec, s[50:51]
	s_cbranch_vccz .LBB0_229
	s_barrier

; #define PG8_STAGE(bufoff, gbase, voff) do { _Pragma("unroll") for (int _i = 0; _i < 2; ++_i) \
;         __builtin_amdgcn_global_load_lds((const unsigned*)((const char*)(gbase) + (voff)[_i]), (PG8_LAS unsigned*)(lds + (bufoff) + ldsw + _i * 8192), 16, 0, 0); } while (0)
; #define PG8_LDA(dst, b, h) do { _Pragma("unroll") for (int m = 0; m < 4; ++m) _Pragma("unroll") for (int k = 0; k < 2; ++k) dst[m][k] = *(const PG8_LAS bf16x8*)(lds + PG8_SA(b, h) + aoff + m * 2048 + k * 1024); } while (0)
; #define PG8_LDB(dst, b, h) do { _Pragma("unroll") for (int n = 0; n < 2; ++n) _Pragma("unroll") for (int k = 0; k < 2; ++k) dst[n][k] = *(const PG8_LAS bf16x8*)(lds + PG8_SB(b, h) + boff + n * 2048 + k * 1024); } while (0)
; #define PG8_MMA(ai, bj, At, Bt) do { __builtin_amdgcn_s_setprio(1); _Pragma("unroll") for (int m = 0; m < 4; ++m) _Pragma("unroll") for (int n = 0; n < 2; ++n) _Pragma("unroll") for (int k = 0; k < 2; ++k) \
;         acc[ai][bj][m][n] = __builtin_amdgcn_mfma_f32_16x16x32_bf16(Bt[n][k], At[m][k], acc[ai][bj][m][n], 0, 0, 0); __builtin_amdgcn_s_setprio(0); } while (0)
; #define PG8_WAIT_V(n) asm volatile("s_waitcnt vmcnt(" #n ")" ::: "memory")
; #define PG8_BAR __builtin_amdgcn_s_barrier()
; template <class Epi, class Sched, bool ALIGN_EPI = false, bool SP2 = false>
; __device__ __forceinline__ void gemm_phase(PG8_LAS unsigned char* lds, const Gemm g, const Sched& S, const Epi& E, int tid_) {
;     ...
;         for (int t = 0; t < nt; t += 2) {
;             const bool last = (t == nt - 2);
;             const char* a1 = cA + (size_t)(t + 1) * kstep;
;             const char* a2 = last ? nA : cA + (size_t)(t + 2) * kstep; const char* b2 = last ? nB : cB + (size_t)(t + 2) * kstep;
;             const char* a3 = a2 + kstep; const char* b3 = b2 + kstep;
;             if (last && has_next) S.a_ready(nxt);
;             if constexpr (SP2) {
;             PG8_LDB(B0, 0, 0); PG8_LDB(B1, 0, 1); PG8_SCHED; PG8_LDA(At, 0, 0); PG8_STAGE(PG8_SA(1, 1), a1 + hstep, voffA);
;             PG8_WAIT_V(8); PG8_WAIT_L(0); PG8_BAR; PG8_MMA(0, 0, At, B0); PG8_MMA(0, 1, At, B1); PG8_BAR; PG8_SCHED;
;             PG8_LDA(At, 0, 1); PG8_STAGE(PG8_SB(0, 0), b2, voffB); PG8_STAGE(PG8_SB(0, 1), b2 + hstep, voffB); PG8_STAGE(PG8_SA(0, 0), a2, voffA);
;             PG8_WAIT_V(8); PG8_WAIT_L(0); PG8_BAR; PG8_MMA(1, 0, At, B0); PG8_MMA(1, 1, At, B1); PG8_BAR; PG8_SCHED;
.LBB0_438:
	v_add_u32_e32 v142, 0x10000, v199
	v_add_u32_e32 v168, 0x14000, v199
	ds_read_b128 v[130:133], v142
	ds_read_b128 v[134:137], v142 offset:1024
	ds_read_b128 v[138:141], v142 offset:2048
	ds_read_b128 v[142:145], v142 offset:3072
	ds_read_b128 v[146:149], v168
	ds_read_b128 v[150:153], v168 offset:1024
	ds_read_b128 v[154:157], v168 offset:2048
	ds_read_b128 v[168:171], v168 offset:3072
	s_add_i32 s74, s64, 2
	s_add_u32 s13, vcc_lo, 0x80
	s_addc_u32 s14, vcc_hi, 0
	s_add_i32 s75, 0, 0x10000
	s_cmp_eq_u32 s73, s64
	s_cselect_b32 s65, s23, s14
	s_cselect_b32 s64, s22, s13
	s_cselect_b32 s91, s61, s81
	s_cselect_b32 s90, s60, s80
	s_add_i32 s13, 0, 0x14000
	v_lshl_add_u64 v[232:233], vcc, 0, v[166:167]
	s_add_i32 m0, s93, 0xc000
	ds_read_b128 v[172:175], v210
	ds_read_b128 v[176:179], v210 offset:1024
	ds_read_b128 v[180:183], v210 offset:2048
	ds_read_b128 v[184:187], v210 offset:3072
	ds_read_b128 v[188:191], v210 offset:4096
	ds_read_b128 v[200:203], v210 offset:5120
	ds_read_b128 v[204:207], v210 offset:6144
	ds_read_b128 v[214:217], v210 offset:7168
	global_load_lds_dwordx4 v[232:233], off
	v_lshl_add_u64 v[232:233], vcc, 0, v[164:165]
	s_add_i32 m0, s93, 0xe000
	s_nop 0
	global_load_lds_dwordx4 v[232:233], off
	s_waitcnt vmcnt(8)
	s_waitcnt lgkmcnt(0)
	s_barrier
	s_setprio 1
	s_waitcnt lgkmcnt(0)
	v_mfma_f32_16x16x32_bf16 v[126:129], v[130:133], v[172:175], v[126:129]
	v_mfma_f32_16x16x32_bf16 v[122:125], v[138:141], v[172:175], v[122:125]
	v_mfma_f32_16x16x32_bf16 v[110:113], v[130:133], v[180:183], v[110:113]
	v_mfma_f32_16x16x32_bf16 v[106:109], v[138:141], v[180:183], v[106:109]
	v_mfma_f32_16x16x32_bf16 v[94:97], v[130:133], v[188:191], v[94:97]
	v_mfma_f32_16x16x32_bf16 v[90:93], v[138:141], v[188:191], v[90:93]
	v_mfma_f32_16x16x32_bf16 v[78:81], v[130:133], v[204:207], v[78:81]
	v_mfma_f32_16x16x32_bf16 v[74:77], v[138:141], v[204:207], v[74:77]
	v_mfma_f32_16x16x32_bf16 v[126:129], v[134:137], v[176:179], v[126:129]
	v_mfma_f32_16x16x32_bf16 v[122:125], v[142:145], v[176:179], v[122:125]
	v_mfma_f32_16x16x32_bf16 v[110:113], v[134:137], v[184:187], v[110:113]
	v_mfma_f32_16x16x32_bf16 v[106:109], v[142:145], v[184:187], v[106:109]
	v_mfma_f32_16x16x32_bf16 v[94:97], v[134:137], v[200:203], v[94:97]
	v_mfma_f32_16x16x32_bf16 v[90:93], v[142:145], v[200:203], v[90:93]
	v_mfma_f32_16x16x32_bf16 v[78:81], v[134:137], v[214:217], v[78:81]
	v_mfma_f32_16x16x32_bf16 v[74:77], v[142:145], v[214:217], v[74:77]
	s_setprio 0
	s_setprio 1
	v_mfma_f32_16x16x32_bf16 v[118:121], v[146:149], v[172:175], v[118:121]
	v_mfma_f32_16x16x32_bf16 v[114:117], v[154:157], v[172:175], v[114:117]
	v_mfma_f32_16x16x32_bf16 v[102:105], v[146:149], v[180:183], v[102:105]
	v_mfma_f32_16x16x32_bf16 v[98:101], v[154:157], v[180:183], v[98:101]
	v_mfma_f32_16x16x32_bf16 v[86:89], v[146:149], v[188:191], v[86:89]
	v_mfma_f32_16x16x32_bf16 v[82:85], v[154:157], v[188:191], v[82:85]
	v_mfma_f32_16x16x32_bf16 v[70:73], v[146:149], v[204:207], v[70:73]
	v_mfma_f32_16x16x32_bf16 v[66:69], v[154:157], v[204:207], v[66:69]
	v_mfma_f32_16x16x32_bf16 v[118:121], v[150:153], v[176:179], v[118:121]
	v_mfma_f32_16x16x32_bf16 v[114:117], v[168:171], v[176:179], v[114:117]
	v_mfma_f32_16x16x32_bf16 v[102:105], v[150:153], v[184:187], v[102:105]
	v_mfma_f32_16x16x32_bf16 v[98:101], v[168:171], v[184:187], v[98:101]
	v_mfma_f32_16x16x32_bf16 v[86:89], v[150:153], v[200:203], v[86:89]
	v_mfma_f32_16x16x32_bf16 v[82:85], v[168:171], v[200:203], v[82:85]
	v_mfma_f32_16x16x32_bf16 v[70:73], v[150:153], v[214:217], v[70:73]
	v_mfma_f32_16x16x32_bf16 v[66:69], v[168:171], v[214:217], v[66:69]
	s_setprio 0
	s_barrier
	s_add_i32 s14, s75, s92
	v_lshl_add_u64 v[232:233], s[90:91], 0, v[0:1]
	s_mov_b32 m0, s14
	ds_read_b128 v[172:175], v210 offset:16384
	ds_read_b128 v[176:179], v210 offset:17408
	ds_read_b128 v[180:183], v210 offset:18432
	ds_read_b128 v[184:187], v210 offset:19456
	ds_read_b128 v[188:191], v210 offset:20480
	ds_read_b128 v[200:203], v210 offset:21504
	ds_read_b128 v[204:207], v210 offset:22528
	ds_read_b128 v[214:217], v210 offset:23552
	global_load_lds_dwordx4 v[232:233], off
	s_add_i32 m0, s14, 0x2000
	v_lshl_add_u64 v[234:235], s[90:91], 0, v[162:163]
	s_add_u32 s90, s90, s50
	s_addc_u32 s91, s91, s51
	s_add_i32 s13, s13, s92
	global_load_lds_dwordx4 v[234:235], off
	v_lshl_add_u64 v[236:237], s[90:91], 0, v[0:1]
	s_mov_b32 m0, s13
	v_lshl_add_u64 v[238:239], s[90:91], 0, v[162:163]
	global_load_lds_dwordx4 v[236:237], off
	s_add_i32 m0, s13, 0x2000
	v_lshl_add_u64 v[240:241], s[64:65], 0, v[158:159]
	global_load_lds_dwordx4 v[238:239], off
	s_mov_b32 m0, s93
	v_lshl_add_u64 v[242:243], s[64:65], 0, v[160:161]
	global_load_lds_dwordx4 v[240:241], off
	s_mov_b32 m0, s94
	s_nop 0
	global_load_lds_dwordx4 v[242:243], off
	s_waitcnt vmcnt(8)
	s_waitcnt lgkmcnt(0)
	s_barrier
; #define PG8_STAGE(bufoff, gbase, voff) do { _Pragma("unroll") for (int _i = 0; _i < 2; ++_i) \
;         __builtin_amdgcn_global_load_lds((const unsigned*)((const char*)(gbase) + (voff)[_i]), (PG8_LAS unsigned*)(lds + (bufoff) + ldsw + _i * 8192), 16, 0, 0); } while (0)
; #define PG8_LDA(dst, b, h) do { _Pragma("unroll") for (int m = 0; m < 4; ++m) _Pragma("unroll") for (int k = 0; k < 2; ++k) dst[m][k] = *(const PG8_LAS bf16x8*)(lds + PG8_SA(b, h) + aoff + m * 2048 + k * 1024); } while (0)
; #define PG8_LDB(dst, b, h) do { _Pragma("unroll") for (int n = 0; n < 2; ++n) _Pragma("unroll") for (int k = 0; k < 2; ++k) dst[n][k] = *(const PG8_LAS bf16x8*)(lds + PG8_SB(b, h) + boff + n * 2048 + k * 1024); } while (0)
; #define PG8_MMA(ai, bj, At, Bt) do { __builtin_amdgcn_s_setprio(1); _Pragma("unroll") for (int m = 0; m < 4; ++m) _Pragma("unroll") for (int n = 0; n < 2; ++n) _Pragma("unroll") for (int k = 0; k < 2; ++k) \
;         acc[ai][bj][m][n] = __builtin_amdgcn_mfma_f32_16x16x32_bf16(Bt[n][k], At[m][k], acc[ai][bj][m][n], 0, 0, 0); __builtin_amdgcn_s_setprio(0); } while (0)
; #define PG8_WAIT_V(n) asm volatile("s_waitcnt vmcnt(" #n ")" ::: "memory")
; #define PG8_WAIT_L(n) asm volatile("s_waitcnt lgkmcnt(" #n ")" ::: "memory")
; #define PG8_BAR __builtin_amdgcn_s_barrier()
; #define PG8_SCHED __builtin_amdgcn_sched_barrier(0)
; template <class Epi, class Sched, bool ALIGN_EPI = false, bool SP2 = false>
; __device__ __forceinline__ void gemm_phase(PG8_LAS unsigned char* lds, const Gemm g, const Sched& S, const Epi& E, int tid_) {
;     ...
;             PG8_WAIT_V(8); PG8_WAIT_L(0); PG8_BAR; PG8_MMA(1, 0, At, B0); PG8_MMA(1, 1, At, B1); PG8_BAR; PG8_SCHED;
;             PG8_LDB(B0, 1, 0); PG8_LDB(B1, 1, 1); PG8_SCHED; PG8_LDA(At, 1, 0); PG8_STAGE(PG8_SA(0, 1), a2 + hstep, voffA);
;             PG8_WAIT_V(8); PG8_WAIT_L(0); PG8_BAR; PG8_MMA(0, 0, At, B0); PG8_MMA(0, 1, At, B1); PG8_BAR; PG8_SCHED;
;             PG8_LDA(At, 1, 1); PG8_STAGE(PG8_SB(1, 0), b3, voffB); PG8_STAGE(PG8_SB(1, 1), b3 + hstep, voffB); PG8_STAGE(PG8_SA(1, 0), a3, voffA);
	s_setprio 1
	s_waitcnt lgkmcnt(0)
	v_mfma_f32_16x16x32_bf16 v[62:65], v[130:133], v[172:175], v[62:65]
	v_mfma_f32_16x16x32_bf16 v[58:61], v[138:141], v[172:175], v[58:61]
	v_mfma_f32_16x16x32_bf16 v[46:49], v[130:133], v[180:183], v[46:49]
	v_mfma_f32_16x16x32_bf16 v[42:45], v[138:141], v[180:183], v[42:45]
	v_mfma_f32_16x16x32_bf16 v[30:33], v[130:133], v[188:191], v[30:33]
	v_mfma_f32_16x16x32_bf16 v[26:29], v[138:141], v[188:191], v[26:29]
	v_mfma_f32_16x16x32_bf16 v[14:17], v[130:133], v[204:207], v[14:17]
	v_mfma_f32_16x16x32_bf16 v[10:13], v[138:141], v[204:207], v[10:13]
	v_mfma_f32_16x16x32_bf16 v[62:65], v[134:137], v[176:179], v[62:65]
	v_mfma_f32_16x16x32_bf16 v[58:61], v[142:145], v[176:179], v[58:61]
	v_mfma_f32_16x16x32_bf16 v[46:49], v[134:137], v[184:187], v[46:49]
	v_mfma_f32_16x16x32_bf16 v[42:45], v[142:145], v[184:187], v[42:45]
	v_mfma_f32_16x16x32_bf16 v[30:33], v[134:137], v[200:203], v[30:33]
	v_mfma_f32_16x16x32_bf16 v[26:29], v[142:145], v[200:203], v[26:29]
	v_mfma_f32_16x16x32_bf16 v[14:17], v[134:137], v[214:217], v[14:17]
	v_mfma_f32_16x16x32_bf16 v[10:13], v[142:145], v[214:217], v[10:13]
	s_setprio 0
	s_setprio 1
	v_mfma_f32_16x16x32_bf16 v[54:57], v[146:149], v[172:175], v[54:57]
	v_mfma_f32_16x16x32_bf16 v[50:53], v[154:157], v[172:175], v[50:53]
	v_mfma_f32_16x16x32_bf16 v[38:41], v[146:149], v[180:183], v[38:41]
	v_mfma_f32_16x16x32_bf16 v[34:37], v[154:157], v[180:183], v[34:37]
	v_mfma_f32_16x16x32_bf16 v[22:25], v[146:149], v[188:191], v[22:25]
	v_mfma_f32_16x16x32_bf16 v[18:21], v[154:157], v[188:191], v[18:21]
	v_mfma_f32_16x16x32_bf16 v[6:9], v[146:149], v[204:207], v[6:9]
	v_mfma_f32_16x16x32_bf16 v[2:5], v[154:157], v[204:207], v[2:5]
	v_mfma_f32_16x16x32_bf16 v[54:57], v[150:153], v[176:179], v[54:57]
	v_mfma_f32_16x16x32_bf16 v[50:53], v[168:171], v[176:179], v[50:53]
	v_mfma_f32_16x16x32_bf16 v[38:41], v[150:153], v[184:187], v[38:41]
	v_mfma_f32_16x16x32_bf16 v[34:37], v[168:171], v[184:187], v[34:37]
	v_mfma_f32_16x16x32_bf16 v[22:25], v[150:153], v[200:203], v[22:25]
	v_mfma_f32_16x16x32_bf16 v[18:21], v[168:171], v[200:203], v[18:21]
	v_mfma_f32_16x16x32_bf16 v[6:9], v[150:153], v[214:217], v[6:9]
	v_mfma_f32_16x16x32_bf16 v[2:5], v[168:171], v[214:217], v[2:5]
	s_setprio 0
	s_barrier
	s_add_i32 s13, 0, 0x18000
	s_add_i32 s14, 0, 0x1c000
	v_add_u32_e32 v142, s13, v199
	v_add_u32_e32 v168, s14, v199
	ds_read_b128 v[130:133], v142
	ds_read_b128 v[134:137], v142 offset:1024
	ds_read_b128 v[138:141], v142 offset:2048
	ds_read_b128 v[142:145], v142 offset:3072
	ds_read_b128 v[146:149], v168
	ds_read_b128 v[150:153], v168 offset:1024
	ds_read_b128 v[154:157], v168 offset:2048
	ds_read_b128 v[168:171], v168 offset:3072
	s_add_u32 s64, s64, s50
	s_addc_u32 s65, s65, s51
	s_mov_b32 m0, s95
	v_lshl_add_u64 v[244:245], s[64:65], 0, v[158:159]
	ds_read_b128 v[172:175], v210 offset:32768
	ds_read_b128 v[176:179], v210 offset:33792
	ds_read_b128 v[180:183], v210 offset:34816
	ds_read_b128 v[184:187], v210 offset:35840
	ds_read_b128 v[188:191], v210 offset:36864
	ds_read_b128 v[200:203], v210 offset:37888
	ds_read_b128 v[204:207], v210 offset:38912
	ds_read_b128 v[214:217], v210 offset:39936
	global_load_lds_dwordx4 v[244:245], off
	v_lshl_add_u64 v[244:245], s[64:65], 0, v[160:161]
	s_mov_b32 m0, s96
	s_nop 0
	global_load_lds_dwordx4 v[244:245], off
	s_waitcnt vmcnt(8)
	s_waitcnt lgkmcnt(0)
	s_barrier
	s_setprio 1
	s_waitcnt lgkmcnt(0)
	v_mfma_f32_16x16x32_bf16 v[126:129], v[130:133], v[172:175], v[126:129]
	v_mfma_f32_16x16x32_bf16 v[122:125], v[138:141], v[172:175], v[122:125]
	v_mfma_f32_16x16x32_bf16 v[110:113], v[130:133], v[180:183], v[110:113]
	v_mfma_f32_16x16x32_bf16 v[106:109], v[138:141], v[180:183], v[106:109]
	v_mfma_f32_16x16x32_bf16 v[94:97], v[130:133], v[188:191], v[94:97]
	v_mfma_f32_16x16x32_bf16 v[90:93], v[138:141], v[188:191], v[90:93]
	v_mfma_f32_16x16x32_bf16 v[78:81], v[130:133], v[204:207], v[78:81]
	v_mfma_f32_16x16x32_bf16 v[74:77], v[138:141], v[204:207], v[74:77]
	v_mfma_f32_16x16x32_bf16 v[126:129], v[134:137], v[176:179], v[126:129]
	v_mfma_f32_16x16x32_bf16 v[122:125], v[142:145], v[176:179], v[122:125]
	v_mfma_f32_16x16x32_bf16 v[110:113], v[134:137], v[184:187], v[110:113]
	v_mfma_f32_16x16x32_bf16 v[106:109], v[142:145], v[184:187], v[106:109]
	v_mfma_f32_16x16x32_bf16 v[94:97], v[134:137], v[200:203], v[94:97]
	v_mfma_f32_16x16x32_bf16 v[90:93], v[142:145], v[200:203], v[90:93]
	v_mfma_f32_16x16x32_bf16 v[78:81], v[134:137], v[214:217], v[78:81]
	v_mfma_f32_16x16x32_bf16 v[74:77], v[142:145], v[214:217], v[74:77]
	s_setprio 0
	s_setprio 1
	v_mfma_f32_16x16x32_bf16 v[118:121], v[146:149], v[172:175], v[118:121]
	v_mfma_f32_16x16x32_bf16 v[114:117], v[154:157], v[172:175], v[114:117]
	v_mfma_f32_16x16x32_bf16 v[102:105], v[146:149], v[180:183], v[102:105]
	v_mfma_f32_16x16x32_bf16 v[98:101], v[154:157], v[180:183], v[98:101]
	v_mfma_f32_16x16x32_bf16 v[86:89], v[146:149], v[188:191], v[86:89]
	v_mfma_f32_16x16x32_bf16 v[82:85], v[154:157], v[188:191], v[82:85]
	v_mfma_f32_16x16x32_bf16 v[70:73], v[146:149], v[204:207], v[70:73]
	v_mfma_f32_16x16x32_bf16 v[66:69], v[154:157], v[204:207], v[66:69]
	v_mfma_f32_16x16x32_bf16 v[118:121], v[150:153], v[176:179], v[118:121]
	v_mfma_f32_16x16x32_bf16 v[114:117], v[168:171], v[176:179], v[114:117]
	v_mfma_f32_16x16x32_bf16 v[102:105], v[150:153], v[184:187], v[102:105]
	v_mfma_f32_16x16x32_bf16 v[98:101], v[168:171], v[184:187], v[98:101]
	v_mfma_f32_16x16x32_bf16 v[86:89], v[150:153], v[200:203], v[86:89]
	v_mfma_f32_16x16x32_bf16 v[82:85], v[168:171], v[200:203], v[82:85]
	v_mfma_f32_16x16x32_bf16 v[70:73], v[150:153], v[214:217], v[70:73]
	v_mfma_f32_16x16x32_bf16 v[66:69], v[168:171], v[214:217], v[66:69]
	s_setprio 0
	s_barrier
; #define PG8_STAGE(bufoff, gbase, voff) do { _Pragma("unroll") for (int _i = 0; _i < 2; ++_i) \
;         __builtin_amdgcn_global_load_lds((const unsigned*)((const char*)(gbase) + (voff)[_i]), (PG8_LAS unsigned*)(lds + (bufoff) + ldsw + _i * 8192), 16, 0, 0); } while (0)
; #define PG8_LDA(dst, b, h) do { _Pragma("unroll") for (int m = 0; m < 4; ++m) _Pragma("unroll") for (int k = 0; k < 2; ++k) dst[m][k] = *(const PG8_LAS bf16x8*)(lds + PG8_SA(b, h) + aoff + m * 2048 + k * 1024); } while (0)
; #define PG8_MMA(ai, bj, At, Bt) do { __builtin_amdgcn_s_setprio(1); _Pragma("unroll") for (int m = 0; m < 4; ++m) _Pragma("unroll") for (int n = 0; n < 2; ++n) _Pragma("unroll") for (int k = 0; k < 2; ++k) \
;         acc[ai][bj][m][n] = __builtin_amdgcn_mfma_f32_16x16x32_bf16(Bt[n][k], At[m][k], acc[ai][bj][m][n], 0, 0, 0); __builtin_amdgcn_s_setprio(0); } while (0)
; #define PG8_WAIT_V(n) asm volatile("s_waitcnt vmcnt(" #n ")" ::: "memory")
; #define PG8_WAIT_L(n) asm volatile("s_waitcnt lgkmcnt(" #n ")" ::: "memory")
; #define PG8_BAR __builtin_amdgcn_s_barrier()
; #define PG8_SCHED __builtin_amdgcn_sched_barrier(0)
; template <class Epi, class Sched, bool ALIGN_EPI = false, bool SP2 = false>
; __device__ __forceinline__ void gemm_phase(PG8_LAS unsigned char* lds, const Gemm g, const Sched& S, const Epi& E, int tid_) {
;     ...
;             PG8_LDA(At, 1, 1); PG8_STAGE(PG8_SB(1, 0), b3, voffB); PG8_STAGE(PG8_SB(1, 1), b3 + hstep, voffB); PG8_STAGE(PG8_SA(1, 0), a3, voffA);
;             PG8_WAIT_V(8); PG8_WAIT_L(0); PG8_BAR; PG8_MMA(1, 0, At, B0); PG8_MMA(1, 1, At, B1); PG8_BAR; PG8_SCHED;
	s_add_i32 s13, s13, s92
	v_lshl_add_u64 v[232:233], v[232:233], 0, s[28:29]
	s_mov_b32 m0, s13
	ds_read_b128 v[172:175], v210 offset:49152
	ds_read_b128 v[176:179], v210 offset:50176
	ds_read_b128 v[180:183], v210 offset:51200
	ds_read_b128 v[184:187], v210 offset:52224
	ds_read_b128 v[188:191], v210 offset:53248
	ds_read_b128 v[200:203], v210 offset:54272
	ds_read_b128 v[204:207], v210 offset:55296
	ds_read_b128 v[214:217], v210 offset:56320
	global_load_lds_dwordx4 v[232:233], off
	v_lshl_add_u64 v[232:233], v[234:235], 0, s[28:29]
	s_add_i32 m0, s13, 0x2000
	s_add_i32 s13, s14, s92
	global_load_lds_dwordx4 v[232:233], off
	v_lshl_add_u64 v[232:233], v[236:237], 0, s[28:29]
	s_mov_b32 m0, s13
	s_nop 0
	global_load_lds_dwordx4 v[232:233], off
	v_lshl_add_u64 v[232:233], v[238:239], 0, s[28:29]
	s_add_i32 m0, s13, 0x2000
	s_nop 0
	global_load_lds_dwordx4 v[232:233], off
	v_lshl_add_u64 v[232:233], v[240:241], 0, s[28:29]
	s_mov_b32 m0, s97
	s_nop 0
	global_load_lds_dwordx4 v[232:233], off
	v_lshl_add_u64 v[232:233], v[242:243], 0, s[28:29]
	s_mov_b32 m0, s98
	s_nop 0
	global_load_lds_dwordx4 v[232:233], off
	s_waitcnt vmcnt(8)
	s_waitcnt lgkmcnt(0)
	s_barrier
	s_setprio 1
	s_waitcnt lgkmcnt(0)
	v_mfma_f32_16x16x32_bf16 v[62:65], v[130:133], v[172:175], v[62:65]
	v_mfma_f32_16x16x32_bf16 v[58:61], v[138:141], v[172:175], v[58:61]
	v_mfma_f32_16x16x32_bf16 v[46:49], v[130:133], v[180:183], v[46:49]
	v_mfma_f32_16x16x32_bf16 v[42:45], v[138:141], v[180:183], v[42:45]
	v_mfma_f32_16x16x32_bf16 v[30:33], v[130:133], v[188:191], v[30:33]
	v_mfma_f32_16x16x32_bf16 v[26:29], v[138:141], v[188:191], v[26:29]
	v_mfma_f32_16x16x32_bf16 v[14:17], v[130:133], v[204:207], v[14:17]
	v_mfma_f32_16x16x32_bf16 v[10:13], v[138:141], v[204:207], v[10:13]
	v_mfma_f32_16x16x32_bf16 v[62:65], v[134:137], v[176:179], v[62:65]
	v_mfma_f32_16x16x32_bf16 v[58:61], v[142:145], v[176:179], v[58:61]
	v_mfma_f32_16x16x32_bf16 v[46:49], v[134:137], v[184:187], v[46:49]
	v_mfma_f32_16x16x32_bf16 v[42:45], v[142:145], v[184:187], v[42:45]
	v_mfma_f32_16x16x32_bf16 v[30:33], v[134:137], v[200:203], v[30:33]
	v_mfma_f32_16x16x32_bf16 v[26:29], v[142:145], v[200:203], v[26:29]
	v_mfma_f32_16x16x32_bf16 v[14:17], v[134:137], v[214:217], v[14:17]
	v_mfma_f32_16x16x32_bf16 v[10:13], v[142:145], v[214:217], v[10:13]
	s_setprio 0
	s_setprio 1
	v_mfma_f32_16x16x32_bf16 v[54:57], v[146:149], v[172:175], v[54:57]
	v_mfma_f32_16x16x32_bf16 v[50:53], v[154:157], v[172:175], v[50:53]
	v_mfma_f32_16x16x32_bf16 v[38:41], v[146:149], v[180:183], v[38:41]
	v_mfma_f32_16x16x32_bf16 v[34:37], v[154:157], v[180:183], v[34:37]
	v_mfma_f32_16x16x32_bf16 v[22:25], v[146:149], v[188:191], v[22:25]
	v_mfma_f32_16x16x32_bf16 v[18:21], v[154:157], v[188:191], v[18:21]
	v_mfma_f32_16x16x32_bf16 v[6:9], v[146:149], v[204:207], v[6:9]
	v_mfma_f32_16x16x32_bf16 v[2:5], v[154:157], v[204:207], v[2:5]
	v_mfma_f32_16x16x32_bf16 v[54:57], v[150:153], v[176:179], v[54:57]
	v_mfma_f32_16x16x32_bf16 v[50:53], v[168:171], v[176:179], v[50:53]
	v_mfma_f32_16x16x32_bf16 v[38:41], v[150:153], v[184:187], v[38:41]
	v_mfma_f32_16x16x32_bf16 v[34:37], v[168:171], v[184:187], v[34:37]
	v_mfma_f32_16x16x32_bf16 v[22:25], v[150:153], v[200:203], v[22:25]
	v_mfma_f32_16x16x32_bf16 v[18:21], v[168:171], v[200:203], v[18:21]
	v_mfma_f32_16x16x32_bf16 v[6:9], v[150:153], v[214:217], v[6:9]
	v_mfma_f32_16x16x32_bf16 v[2:5], v[168:171], v[214:217], v[2:5]
	s_setprio 0
	s_barrier
	s_add_u32 s80, s80, 0x100
	s_addc_u32 s81, s81, 0
	s_add_u32 vcc_lo, vcc_lo, 0x100
	s_addc_u32 vcc_hi, vcc_hi, 0
	s_cmp_ge_i32 s74, s86
	s_mov_b32 s64, s74
	s_cbranch_scc0 .LBB0_438
	s_movk_i32 s90, 0x7ff
	s_movk_i32 s91, 0x80
	s_and_b64 vcc, exec, s[56:57]
	s_cbranch_vccz .LBB0_441

; #define PG8_STAGE(bufoff, gbase, voff) do { _Pragma("unroll") for (int _i = 0; _i < 2; ++_i) \
;         __builtin_amdgcn_global_load_lds((const unsigned*)((const char*)(gbase) + (voff)[_i]), (PG8_LAS unsigned*)(lds + (bufoff) + ldsw + _i * 8192), 16, 0, 0); } while (0)
; #define PG8_LDA(dst, b, h) do { _Pragma("unroll") for (int m = 0; m < 4; ++m) _Pragma("unroll") for (int k = 0; k < 2; ++k) dst[m][k] = *(const PG8_LAS bf16x8*)(lds + PG8_SA(b, h) + aoff + m * 2048 + k * 1024); } while (0)
; #define PG8_LDB(dst, b, h) do { _Pragma("unroll") for (int n = 0; n < 2; ++n) _Pragma("unroll") for (int k = 0; k < 2; ++k) dst[n][k] = *(const PG8_LAS bf16x8*)(lds + PG8_SB(b, h) + boff + n * 2048 + k * 1024); } while (0)
; #define PG8_MMA(ai, bj, At, Bt) do { __builtin_amdgcn_s_setprio(1); _Pragma("unroll") for (int m = 0; m < 4; ++m) _Pragma("unroll") for (int n = 0; n < 2; ++n) _Pragma("unroll") for (int k = 0; k < 2; ++k) \
;         acc[ai][bj][m][n] = __builtin_amdgcn_mfma_f32_16x16x32_bf16(Bt[n][k], At[m][k], acc[ai][bj][m][n], 0, 0, 0); __builtin_amdgcn_s_setprio(0); } while (0)
; #define PG8_WAIT_V(n) asm volatile("s_waitcnt vmcnt(" #n ")" ::: "memory")
; #define PG8_BAR __builtin_amdgcn_s_barrier()
; template <class Epi, class Sched, bool ALIGN_EPI = false, bool SP2 = false>
; __device__ __forceinline__ void gemm_phase(PG8_LAS unsigned char* lds, const Gemm g, const Sched& S, const Epi& E, int tid_) {
;     ...
;         for (int t = 0; t < nt; t += 2) {
;             const bool last = (t == nt - 2);
;             const char* a1 = cA + (size_t)(t + 1) * kstep;
;             const char* a2 = last ? nA : cA + (size_t)(t + 2) * kstep; const char* b2 = last ? nB : cB + (size_t)(t + 2) * kstep;
;             const char* a3 = a2 + kstep; const char* b3 = b2 + kstep;
;             if (last && has_next) S.a_ready(nxt);
;             if constexpr (SP2) {
;             PG8_LDB(B0, 0, 0); PG8_LDB(B1, 0, 1); PG8_SCHED; PG8_LDA(At, 0, 0); PG8_STAGE(PG8_SA(1, 1), a1 + hstep, voffA);
;             PG8_WAIT_V(8); PG8_WAIT_L(0); PG8_BAR; PG8_MMA(0, 0, At, B0); PG8_MMA(0, 1, At, B1); PG8_BAR; PG8_SCHED;
;             PG8_LDA(At, 0, 1); PG8_STAGE(PG8_SB(0, 0), b2, voffB); PG8_STAGE(PG8_SB(0, 1), b2 + hstep, voffB); PG8_STAGE(PG8_SA(0, 0), a2, voffA);
;             PG8_WAIT_V(8); PG8_WAIT_L(0); PG8_BAR; PG8_MMA(1, 0, At, B0); PG8_MMA(1, 1, At, B1); PG8_BAR; PG8_SCHED;
.LBB0_526:
	v_add_u32_e32 v156, 0x10000, v145
	v_add_u32_e32 v172, 0x14000, v145
	ds_read_b128 v[140:143], v156
	ds_read_b128 v[148:151], v156 offset:1024
	ds_read_b128 v[152:155], v156 offset:2048
	ds_read_b128 v[156:159], v156 offset:3072
	ds_read_b128 v[160:163], v172
	ds_read_b128 v[164:167], v172 offset:1024
	ds_read_b128 v[168:171], v172 offset:2048
	ds_read_b128 v[172:175], v172 offset:3072
	s_add_u32 s21, s54, 0xfffc0080
	s_addc_u32 s56, s55, -1
	s_add_i32 s75, 0, 0x10000
	s_cmp_eq_u32 s74, 12
	s_cselect_b32 s59, s47, s56
	s_cselect_b32 s58, s70, s21
	s_cselect_b32 s57, s45, s73
	s_cselect_b32 s56, s71, s72
	s_add_i32 s21, 0, 0x14000
	v_lshl_add_u64 v[232:233], s[54:55], 0, v[138:139]
	s_add_i32 m0, s13, 0xc000
	ds_read_b128 v[176:179], v147
	ds_read_b128 v[180:183], v147 offset:1024
	ds_read_b128 v[184:187], v147 offset:2048
	ds_read_b128 v[188:191], v147 offset:3072
	ds_read_b128 v[200:203], v147 offset:4096
	ds_read_b128 v[204:207], v147 offset:5120
	ds_read_b128 v[208:211], v147 offset:6144
	ds_read_b128 v[214:217], v147 offset:7168
	global_load_lds_dwordx4 v[232:233], off
	v_lshl_add_u64 v[232:233], s[54:55], 0, v[136:137]
	s_add_i32 m0, s13, 0xe000
	s_nop 0
	global_load_lds_dwordx4 v[232:233], off
	s_waitcnt vmcnt(8)
	s_waitcnt lgkmcnt(0)
	s_barrier
	s_setprio 1
	s_waitcnt lgkmcnt(0)
	v_mfma_f32_16x16x32_bf16 v[126:129], v[140:143], v[176:179], v[126:129]
	v_mfma_f32_16x16x32_bf16 v[118:121], v[152:155], v[176:179], v[118:121]
	v_mfma_f32_16x16x32_bf16 v[110:113], v[140:143], v[184:187], v[110:113]
	v_mfma_f32_16x16x32_bf16 v[102:105], v[152:155], v[184:187], v[102:105]
	v_mfma_f32_16x16x32_bf16 v[94:97], v[140:143], v[200:203], v[94:97]
	v_mfma_f32_16x16x32_bf16 v[86:89], v[152:155], v[200:203], v[86:89]
	v_mfma_f32_16x16x32_bf16 v[78:81], v[140:143], v[208:211], v[78:81]
	v_mfma_f32_16x16x32_bf16 v[70:73], v[152:155], v[208:211], v[70:73]
	v_mfma_f32_16x16x32_bf16 v[126:129], v[148:151], v[180:183], v[126:129]
	v_mfma_f32_16x16x32_bf16 v[118:121], v[156:159], v[180:183], v[118:121]
	v_mfma_f32_16x16x32_bf16 v[110:113], v[148:151], v[188:191], v[110:113]
	v_mfma_f32_16x16x32_bf16 v[102:105], v[156:159], v[188:191], v[102:105]
	v_mfma_f32_16x16x32_bf16 v[94:97], v[148:151], v[204:207], v[94:97]
	v_mfma_f32_16x16x32_bf16 v[86:89], v[156:159], v[204:207], v[86:89]
	v_mfma_f32_16x16x32_bf16 v[78:81], v[148:151], v[214:217], v[78:81]
	v_mfma_f32_16x16x32_bf16 v[70:73], v[156:159], v[214:217], v[70:73]
	s_setprio 0
	s_setprio 1
	v_mfma_f32_16x16x32_bf16 v[122:125], v[160:163], v[176:179], v[122:125]
	v_mfma_f32_16x16x32_bf16 v[114:117], v[168:171], v[176:179], v[114:117]
	v_mfma_f32_16x16x32_bf16 v[106:109], v[160:163], v[184:187], v[106:109]
	v_mfma_f32_16x16x32_bf16 v[98:101], v[168:171], v[184:187], v[98:101]
	v_mfma_f32_16x16x32_bf16 v[90:93], v[160:163], v[200:203], v[90:93]
	v_mfma_f32_16x16x32_bf16 v[82:85], v[168:171], v[200:203], v[82:85]
	v_mfma_f32_16x16x32_bf16 v[74:77], v[160:163], v[208:211], v[74:77]
	v_mfma_f32_16x16x32_bf16 v[66:69], v[168:171], v[208:211], v[66:69]
	v_mfma_f32_16x16x32_bf16 v[122:125], v[164:167], v[180:183], v[122:125]
	v_mfma_f32_16x16x32_bf16 v[114:117], v[172:175], v[180:183], v[114:117]
	v_mfma_f32_16x16x32_bf16 v[106:109], v[164:167], v[188:191], v[106:109]
	v_mfma_f32_16x16x32_bf16 v[98:101], v[172:175], v[188:191], v[98:101]
	v_mfma_f32_16x16x32_bf16 v[90:93], v[164:167], v[204:207], v[90:93]
	v_mfma_f32_16x16x32_bf16 v[82:85], v[172:175], v[204:207], v[82:85]
	v_mfma_f32_16x16x32_bf16 v[74:77], v[164:167], v[214:217], v[74:77]
	v_mfma_f32_16x16x32_bf16 v[66:69], v[172:175], v[214:217], v[66:69]
	s_setprio 0
	s_barrier
	s_add_i32 s75, s75, s9
	v_lshl_add_u64 v[232:233], s[56:57], 0, v[0:1]
	s_mov_b32 m0, s75
	ds_read_b128 v[176:179], v147 offset:16384
	ds_read_b128 v[180:183], v147 offset:17408
	ds_read_b128 v[184:187], v147 offset:18432
	ds_read_b128 v[188:191], v147 offset:19456
	ds_read_b128 v[200:203], v147 offset:20480
	ds_read_b128 v[204:207], v147 offset:21504
	ds_read_b128 v[208:211], v147 offset:22528
	ds_read_b128 v[214:217], v147 offset:23552
	global_load_lds_dwordx4 v[232:233], off
	s_add_i32 m0, s75, 0x2000
	s_add_u32 s80, s56, 0x40000
	v_lshl_add_u64 v[234:235], s[56:57], 0, v[130:131]
	s_addc_u32 s81, s57, 0
	s_add_i32 s21, s21, s9
	global_load_lds_dwordx4 v[234:235], off
	v_lshl_add_u64 v[236:237], s[80:81], 0, v[0:1]
	s_mov_b32 m0, s21
	v_lshl_add_u64 v[238:239], s[58:59], 0, v[132:133]
	global_load_lds_dwordx4 v[236:237], off
	v_lshl_add_u64 v[236:237], s[80:81], 0, v[130:131]
	s_add_i32 m0, s21, 0x2000
	s_nop 0
	global_load_lds_dwordx4 v[236:237], off
	v_lshl_add_u64 v[236:237], s[58:59], 0, v[134:135]
	s_mov_b32 m0, s13
	s_nop 0
	global_load_lds_dwordx4 v[236:237], off
	s_mov_b32 m0, s14
	s_nop 0
	global_load_lds_dwordx4 v[238:239], off
	s_waitcnt vmcnt(8)
	s_waitcnt lgkmcnt(0)
	s_barrier
; #define PG8_STAGE(bufoff, gbase, voff) do { _Pragma("unroll") for (int _i = 0; _i < 2; ++_i) \
;         __builtin_amdgcn_global_load_lds((const unsigned*)((const char*)(gbase) + (voff)[_i]), (PG8_LAS unsigned*)(lds + (bufoff) + ldsw + _i * 8192), 16, 0, 0); } while (0)
; #define PG8_LDA(dst, b, h) do { _Pragma("unroll") for (int m = 0; m < 4; ++m) _Pragma("unroll") for (int k = 0; k < 2; ++k) dst[m][k] = *(const PG8_LAS bf16x8*)(lds + PG8_SA(b, h) + aoff + m * 2048 + k * 1024); } while (0)
; #define PG8_LDB(dst, b, h) do { _Pragma("unroll") for (int n = 0; n < 2; ++n) _Pragma("unroll") for (int k = 0; k < 2; ++k) dst[n][k] = *(const PG8_LAS bf16x8*)(lds + PG8_SB(b, h) + boff + n * 2048 + k * 1024); } while (0)
; #define PG8_MMA(ai, bj, At, Bt) do { __builtin_amdgcn_s_setprio(1); _Pragma("unroll") for (int m = 0; m < 4; ++m) _Pragma("unroll") for (int n = 0; n < 2; ++n) _Pragma("unroll") for (int k = 0; k < 2; ++k) \
;         acc[ai][bj][m][n] = __builtin_amdgcn_mfma_f32_16x16x32_bf16(Bt[n][k], At[m][k], acc[ai][bj][m][n], 0, 0, 0); __builtin_amdgcn_s_setprio(0); } while (0)
; #define PG8_WAIT_V(n) asm volatile("s_waitcnt vmcnt(" #n ")" ::: "memory")
; #define PG8_WAIT_L(n) asm volatile("s_waitcnt lgkmcnt(" #n ")" ::: "memory")
; #define PG8_BAR __builtin_amdgcn_s_barrier()
; #define PG8_SCHED __builtin_amdgcn_sched_barrier(0)
; template <class Epi, class Sched, bool ALIGN_EPI = false, bool SP2 = false>
; __device__ __forceinline__ void gemm_phase(PG8_LAS unsigned char* lds, const Gemm g, const Sched& S, const Epi& E, int tid_) {
;     ...
;             PG8_WAIT_V(8); PG8_WAIT_L(0); PG8_BAR; PG8_MMA(1, 0, At, B0); PG8_MMA(1, 1, At, B1); PG8_BAR; PG8_SCHED;
;             PG8_LDB(B0, 1, 0); PG8_LDB(B1, 1, 1); PG8_SCHED; PG8_LDA(At, 1, 0); PG8_STAGE(PG8_SA(0, 1), a2 + hstep, voffA);
;             PG8_WAIT_V(8); PG8_WAIT_L(0); PG8_BAR; PG8_MMA(0, 0, At, B0); PG8_MMA(0, 1, At, B1); PG8_BAR; PG8_SCHED;
;             PG8_LDA(At, 1, 1); PG8_STAGE(PG8_SB(1, 0), b3, voffB); PG8_STAGE(PG8_SB(1, 1), b3 + hstep, voffB); PG8_STAGE(PG8_SA(1, 0), a3, voffA);
	s_setprio 1
	s_waitcnt lgkmcnt(0)
	v_mfma_f32_16x16x32_bf16 v[62:65], v[140:143], v[176:179], v[62:65]
	v_mfma_f32_16x16x32_bf16 v[54:57], v[152:155], v[176:179], v[54:57]
	v_mfma_f32_16x16x32_bf16 v[46:49], v[140:143], v[184:187], v[46:49]
	v_mfma_f32_16x16x32_bf16 v[38:41], v[152:155], v[184:187], v[38:41]
	v_mfma_f32_16x16x32_bf16 v[30:33], v[140:143], v[200:203], v[30:33]
	v_mfma_f32_16x16x32_bf16 v[22:25], v[152:155], v[200:203], v[22:25]
	v_mfma_f32_16x16x32_bf16 v[14:17], v[140:143], v[208:211], v[14:17]
	v_mfma_f32_16x16x32_bf16 v[6:9], v[152:155], v[208:211], v[6:9]
	v_mfma_f32_16x16x32_bf16 v[62:65], v[148:151], v[180:183], v[62:65]
	v_mfma_f32_16x16x32_bf16 v[54:57], v[156:159], v[180:183], v[54:57]
	v_mfma_f32_16x16x32_bf16 v[46:49], v[148:151], v[188:191], v[46:49]
	v_mfma_f32_16x16x32_bf16 v[38:41], v[156:159], v[188:191], v[38:41]
	v_mfma_f32_16x16x32_bf16 v[30:33], v[148:151], v[204:207], v[30:33]
	v_mfma_f32_16x16x32_bf16 v[22:25], v[156:159], v[204:207], v[22:25]
	v_mfma_f32_16x16x32_bf16 v[14:17], v[148:151], v[214:217], v[14:17]
	v_mfma_f32_16x16x32_bf16 v[6:9], v[156:159], v[214:217], v[6:9]
	s_setprio 0
	s_setprio 1
	v_mfma_f32_16x16x32_bf16 v[58:61], v[160:163], v[176:179], v[58:61]
	v_mfma_f32_16x16x32_bf16 v[50:53], v[168:171], v[176:179], v[50:53]
	v_mfma_f32_16x16x32_bf16 v[42:45], v[160:163], v[184:187], v[42:45]
	v_mfma_f32_16x16x32_bf16 v[34:37], v[168:171], v[184:187], v[34:37]
	v_mfma_f32_16x16x32_bf16 v[26:29], v[160:163], v[200:203], v[26:29]
	v_mfma_f32_16x16x32_bf16 v[18:21], v[168:171], v[200:203], v[18:21]
	v_mfma_f32_16x16x32_bf16 v[10:13], v[160:163], v[208:211], v[10:13]
	v_mfma_f32_16x16x32_bf16 v[2:5], v[168:171], v[208:211], v[2:5]
	v_mfma_f32_16x16x32_bf16 v[58:61], v[164:167], v[180:183], v[58:61]
	v_mfma_f32_16x16x32_bf16 v[50:53], v[172:175], v[180:183], v[50:53]
	v_mfma_f32_16x16x32_bf16 v[42:45], v[164:167], v[188:191], v[42:45]
	v_mfma_f32_16x16x32_bf16 v[34:37], v[172:175], v[188:191], v[34:37]
	v_mfma_f32_16x16x32_bf16 v[26:29], v[164:167], v[204:207], v[26:29]
	v_mfma_f32_16x16x32_bf16 v[18:21], v[172:175], v[204:207], v[18:21]
	v_mfma_f32_16x16x32_bf16 v[10:13], v[164:167], v[214:217], v[10:13]
	v_mfma_f32_16x16x32_bf16 v[2:5], v[172:175], v[214:217], v[2:5]
	s_setprio 0
	s_barrier
	s_add_i32 s21, 0, 0x18000
	s_add_i32 s75, 0, 0x1c000
	v_add_u32_e32 v156, s21, v145
	v_add_u32_e32 v172, s75, v145
	ds_read_b128 v[140:143], v156
	ds_read_b128 v[148:151], v156 offset:1024
	ds_read_b128 v[152:155], v156 offset:2048
	ds_read_b128 v[156:159], v156 offset:3072
	ds_read_b128 v[160:163], v172
	ds_read_b128 v[164:167], v172 offset:1024
	ds_read_b128 v[168:171], v172 offset:2048
	ds_read_b128 v[172:175], v172 offset:3072
	s_add_u32 s58, s58, 0x40000
	s_addc_u32 s59, s59, 0
	s_mov_b32 m0, s15
	v_lshl_add_u64 v[240:241], s[58:59], 0, v[134:135]
	ds_read_b128 v[176:179], v147 offset:32768
	ds_read_b128 v[180:183], v147 offset:33792
	ds_read_b128 v[184:187], v147 offset:34816
	ds_read_b128 v[188:191], v147 offset:35840
	ds_read_b128 v[200:203], v147 offset:36864
	ds_read_b128 v[204:207], v147 offset:37888
	ds_read_b128 v[208:211], v147 offset:38912
	ds_read_b128 v[214:217], v147 offset:39936
	global_load_lds_dwordx4 v[240:241], off
	v_lshl_add_u64 v[240:241], s[58:59], 0, v[132:133]
	s_mov_b32 m0, s60
	s_nop 0
	global_load_lds_dwordx4 v[240:241], off
	s_waitcnt vmcnt(8)
	s_waitcnt lgkmcnt(0)
	s_barrier
	s_setprio 1
	s_waitcnt lgkmcnt(0)
	v_mfma_f32_16x16x32_bf16 v[126:129], v[140:143], v[176:179], v[126:129]
	v_mfma_f32_16x16x32_bf16 v[118:121], v[152:155], v[176:179], v[118:121]
	v_mfma_f32_16x16x32_bf16 v[110:113], v[140:143], v[184:187], v[110:113]
	v_mfma_f32_16x16x32_bf16 v[102:105], v[152:155], v[184:187], v[102:105]
	v_mfma_f32_16x16x32_bf16 v[94:97], v[140:143], v[200:203], v[94:97]
	v_mfma_f32_16x16x32_bf16 v[86:89], v[152:155], v[200:203], v[86:89]
	v_mfma_f32_16x16x32_bf16 v[78:81], v[140:143], v[208:211], v[78:81]
	v_mfma_f32_16x16x32_bf16 v[70:73], v[152:155], v[208:211], v[70:73]
	v_mfma_f32_16x16x32_bf16 v[126:129], v[148:151], v[180:183], v[126:129]
	v_mfma_f32_16x16x32_bf16 v[118:121], v[156:159], v[180:183], v[118:121]
	v_mfma_f32_16x16x32_bf16 v[110:113], v[148:151], v[188:191], v[110:113]
	v_mfma_f32_16x16x32_bf16 v[102:105], v[156:159], v[188:191], v[102:105]
	v_mfma_f32_16x16x32_bf16 v[94:97], v[148:151], v[204:207], v[94:97]
	v_mfma_f32_16x16x32_bf16 v[86:89], v[156:159], v[204:207], v[86:89]
	v_mfma_f32_16x16x32_bf16 v[78:81], v[148:151], v[214:217], v[78:81]
	v_mfma_f32_16x16x32_bf16 v[70:73], v[156:159], v[214:217], v[70:73]
	s_setprio 0
	s_setprio 1
	v_mfma_f32_16x16x32_bf16 v[122:125], v[160:163], v[176:179], v[122:125]
	v_mfma_f32_16x16x32_bf16 v[114:117], v[168:171], v[176:179], v[114:117]
	v_mfma_f32_16x16x32_bf16 v[106:109], v[160:163], v[184:187], v[106:109]
	v_mfma_f32_16x16x32_bf16 v[98:101], v[168:171], v[184:187], v[98:101]
	v_mfma_f32_16x16x32_bf16 v[90:93], v[160:163], v[200:203], v[90:93]
	v_mfma_f32_16x16x32_bf16 v[82:85], v[168:171], v[200:203], v[82:85]
	v_mfma_f32_16x16x32_bf16 v[74:77], v[160:163], v[208:211], v[74:77]
	v_mfma_f32_16x16x32_bf16 v[66:69], v[168:171], v[208:211], v[66:69]
	v_mfma_f32_16x16x32_bf16 v[122:125], v[164:167], v[180:183], v[122:125]
	v_mfma_f32_16x16x32_bf16 v[114:117], v[172:175], v[180:183], v[114:117]
	v_mfma_f32_16x16x32_bf16 v[106:109], v[164:167], v[188:191], v[106:109]
	v_mfma_f32_16x16x32_bf16 v[98:101], v[172:175], v[188:191], v[98:101]
	v_mfma_f32_16x16x32_bf16 v[90:93], v[164:167], v[204:207], v[90:93]
	v_mfma_f32_16x16x32_bf16 v[82:85], v[172:175], v[204:207], v[82:85]
	v_mfma_f32_16x16x32_bf16 v[74:77], v[164:167], v[214:217], v[74:77]
	v_mfma_f32_16x16x32_bf16 v[66:69], v[172:175], v[214:217], v[66:69]
	s_setprio 0
	s_barrier
; #define PG8_STAGE(bufoff, gbase, voff) do { _Pragma("unroll") for (int _i = 0; _i < 2; ++_i) \
;         __builtin_amdgcn_global_load_lds((const unsigned*)((const char*)(gbase) + (voff)[_i]), (PG8_LAS unsigned*)(lds + (bufoff) + ldsw + _i * 8192), 16, 0, 0); } while (0)
; #define PG8_LDA(dst, b, h) do { _Pragma("unroll") for (int m = 0; m < 4; ++m) _Pragma("unroll") for (int k = 0; k < 2; ++k) dst[m][k] = *(const PG8_LAS bf16x8*)(lds + PG8_SA(b, h) + aoff + m * 2048 + k * 1024); } while (0)
; #define PG8_MMA(ai, bj, At, Bt) do { __builtin_amdgcn_s_setprio(1); _Pragma("unroll") for (int m = 0; m < 4; ++m) _Pragma("unroll") for (int n = 0; n < 2; ++n) _Pragma("unroll") for (int k = 0; k < 2; ++k) \
;         acc[ai][bj][m][n] = __builtin_amdgcn_mfma_f32_16x16x32_bf16(Bt[n][k], At[m][k], acc[ai][bj][m][n], 0, 0, 0); __builtin_amdgcn_s_setprio(0); } while (0)
; #define PG8_WAIT_V(n) asm volatile("s_waitcnt vmcnt(" #n ")" ::: "memory")
; #define PG8_WAIT_L(n) asm volatile("s_waitcnt lgkmcnt(" #n ")" ::: "memory")
; #define PG8_BAR __builtin_amdgcn_s_barrier()
; #define PG8_SCHED __builtin_amdgcn_sched_barrier(0)
; template <class Epi, class Sched, bool ALIGN_EPI = false, bool SP2 = false>
; __device__ __forceinline__ void gemm_phase(PG8_LAS unsigned char* lds, const Gemm g, const Sched& S, const Epi& E, int tid_) {
;     ...
;             PG8_LDA(At, 1, 1); PG8_STAGE(PG8_SB(1, 0), b3, voffB); PG8_STAGE(PG8_SB(1, 1), b3 + hstep, voffB); PG8_STAGE(PG8_SA(1, 0), a3, voffA);
;             PG8_WAIT_V(8); PG8_WAIT_L(0); PG8_BAR; PG8_MMA(1, 0, At, B0); PG8_MMA(1, 1, At, B1); PG8_BAR; PG8_SCHED;
	s_add_i32 s21, s21, s9
	v_lshl_add_u64 v[232:233], v[232:233], 0, s[28:29]
	s_mov_b32 m0, s21
	ds_read_b128 v[176:179], v147 offset:49152
	ds_read_b128 v[180:183], v147 offset:50176
	ds_read_b128 v[184:187], v147 offset:51200
	ds_read_b128 v[188:191], v147 offset:52224
	ds_read_b128 v[200:203], v147 offset:53248
	ds_read_b128 v[204:207], v147 offset:54272
	ds_read_b128 v[208:211], v147 offset:55296
	ds_read_b128 v[214:217], v147 offset:56320
	global_load_lds_dwordx4 v[232:233], off
	s_add_i32 m0, s21, 0x2000
	s_add_u32 s56, s56, 0x40080
	v_lshl_add_u64 v[232:233], v[234:235], 0, s[28:29]
	s_addc_u32 s57, s57, 0
	s_add_i32 s21, s75, s9
	global_load_lds_dwordx4 v[232:233], off
	v_lshl_add_u64 v[232:233], s[56:57], 0, v[0:1]
	s_mov_b32 m0, s21
	s_nop 0
	global_load_lds_dwordx4 v[232:233], off
	v_lshl_add_u64 v[232:233], s[56:57], 0, v[130:131]
	s_add_i32 m0, s21, 0x2000
	s_nop 0
	global_load_lds_dwordx4 v[232:233], off
	v_lshl_add_u64 v[232:233], v[236:237], 0, s[28:29]
	s_mov_b32 m0, s61
	s_nop 0
	global_load_lds_dwordx4 v[232:233], off
	v_lshl_add_u64 v[232:233], v[238:239], 0, s[28:29]
	s_mov_b32 m0, s64
	s_nop 0
	global_load_lds_dwordx4 v[232:233], off
	s_waitcnt vmcnt(8)
	s_waitcnt lgkmcnt(0)
	s_barrier
	s_setprio 1
	s_waitcnt lgkmcnt(0)
	v_mfma_f32_16x16x32_bf16 v[62:65], v[140:143], v[176:179], v[62:65]
	v_mfma_f32_16x16x32_bf16 v[54:57], v[152:155], v[176:179], v[54:57]
	v_mfma_f32_16x16x32_bf16 v[46:49], v[140:143], v[184:187], v[46:49]
	v_mfma_f32_16x16x32_bf16 v[38:41], v[152:155], v[184:187], v[38:41]
	v_mfma_f32_16x16x32_bf16 v[30:33], v[140:143], v[200:203], v[30:33]
	v_mfma_f32_16x16x32_bf16 v[22:25], v[152:155], v[200:203], v[22:25]
	v_mfma_f32_16x16x32_bf16 v[14:17], v[140:143], v[208:211], v[14:17]
	v_mfma_f32_16x16x32_bf16 v[6:9], v[152:155], v[208:211], v[6:9]
	v_mfma_f32_16x16x32_bf16 v[62:65], v[148:151], v[180:183], v[62:65]
	v_mfma_f32_16x16x32_bf16 v[54:57], v[156:159], v[180:183], v[54:57]
	v_mfma_f32_16x16x32_bf16 v[46:49], v[148:151], v[188:191], v[46:49]
	v_mfma_f32_16x16x32_bf16 v[38:41], v[156:159], v[188:191], v[38:41]
	v_mfma_f32_16x16x32_bf16 v[30:33], v[148:151], v[204:207], v[30:33]
	v_mfma_f32_16x16x32_bf16 v[22:25], v[156:159], v[204:207], v[22:25]
	v_mfma_f32_16x16x32_bf16 v[14:17], v[148:151], v[214:217], v[14:17]
	v_mfma_f32_16x16x32_bf16 v[6:9], v[156:159], v[214:217], v[6:9]
	s_setprio 0
	s_setprio 1
	v_mfma_f32_16x16x32_bf16 v[58:61], v[160:163], v[176:179], v[58:61]
	v_mfma_f32_16x16x32_bf16 v[50:53], v[168:171], v[176:179], v[50:53]
	v_mfma_f32_16x16x32_bf16 v[42:45], v[160:163], v[184:187], v[42:45]
	v_mfma_f32_16x16x32_bf16 v[34:37], v[168:171], v[184:187], v[34:37]
	v_mfma_f32_16x16x32_bf16 v[26:29], v[160:163], v[200:203], v[26:29]
	v_mfma_f32_16x16x32_bf16 v[18:21], v[168:171], v[200:203], v[18:21]
	v_mfma_f32_16x16x32_bf16 v[10:13], v[160:163], v[208:211], v[10:13]
	v_mfma_f32_16x16x32_bf16 v[2:5], v[168:171], v[208:211], v[2:5]
	v_mfma_f32_16x16x32_bf16 v[58:61], v[164:167], v[180:183], v[58:61]
	v_mfma_f32_16x16x32_bf16 v[50:53], v[172:175], v[180:183], v[50:53]
	v_mfma_f32_16x16x32_bf16 v[42:45], v[164:167], v[188:191], v[42:45]
	v_mfma_f32_16x16x32_bf16 v[34:37], v[172:175], v[188:191], v[34:37]
	v_mfma_f32_16x16x32_bf16 v[26:29], v[164:167], v[204:207], v[26:29]
	v_mfma_f32_16x16x32_bf16 v[18:21], v[172:175], v[204:207], v[18:21]
	v_mfma_f32_16x16x32_bf16 v[10:13], v[164:167], v[214:217], v[10:13]
	v_mfma_f32_16x16x32_bf16 v[2:5], v[172:175], v[214:217], v[2:5]
	s_setprio 0
	s_barrier
	s_add_i32 s74, s74, 2
	s_add_u32 s72, s72, 0x100
	s_addc_u32 s73, s73, 0
	s_add_u32 s54, s54, 0x100
	s_addc_u32 s55, s55, 0
	s_cmp_gt_u32 s74, 13
	s_cbranch_scc0 .LBB0_526
	s_and_b64 vcc, exec, s[42:43]
	s_cbranch_vccz .LBB0_529
	s_barrier
